# v102 plus fox_attn gm/km wave maxima via DPP row reduction + v_readlane instead of two 6-step ds_bpermute butterflies
# speedup vs baseline: 1.0147x; 1.0119x over previous
.LBB0_266:
	s_or_b64 exec, exec, s[10:11]
	v_and_b32_e32 v185, 63, v24
	s_waitcnt lgkmcnt(0)
	s_add_u32 s40, s6, s70
	s_addc_u32 s41, s7, s71
	v_lshlrev_b32_e32 v0, 2, v185
	s_nop 0
	s_add_u32 s20, s2, s70
	s_addc_u32 s21, s3, s71
	s_nop 0
	s_waitcnt vmcnt(0)
	v_mov_b32_e32 v2, v31
	v_mov_b32_e32 v0, v32
	v_and_b32_e32 v5, 64, v174
	v_add_u32_e32 v5, 64, v5
	v_xor_b32_e32 v6, 1, v174
	v_cmp_lt_i32_e32 vcc, v6, v5
	s_ashr_i32 s54, s45, 6
	s_lshl_b32 s58, s54, 5
	v_cndmask_b32_e32 v6, v174, v6, vcc
	v_lshlrev_b32_e32 v147, 2, v6
	s_add_i32 s58, s58, s47
	s_ashr_i32 s59, s58, 6
	s_ashr_i32 s60, s85, 7
	s_ashr_i32 s61, s60, 31
	s_lshl_b64 s[60:61], s[60:61], 13
	s_lshl_b32 s62, s44, 6
	s_and_b32 s62, s62, 0xc0
	s_ashr_i32 s63, s58, 31
	s_add_u32 s60, s60, s58
	s_addc_u32 s61, s61, s63
	v_and_b32_e32 v84, 31, v24
	v_or_b32_e32 v84, s60, v84
	v_mov_b64_e32 v[86:87], s[26:27]
	v_mad_u64_u32 v[86:87], s[76:77], v84, s18, v[86:87]
	v_mov_b32_e32 v85, 0x1e00
	v_mad_i32_i24 v87, s61, v85, v87
	s_lshl_b32 s62, s62, 1
	s_mov_b32 s63, 0
	v_lshl_add_u64 v[86:87], v[86:87], 0, s[62:63]
	v_lshrrev_b32_e32 v88, 5, v185
	v_lshlrev_b32_e32 v88, 4, v88
	v_mov_b32_e32 v89, v1
	v_lshl_add_u64 v[86:87], v[86:87], 0, v[88:89]
	v_and_b32_e32 v90, 32, v185
	global_load_dwordx4 v[96:99], v[86:87], off offset:2048
	global_load_dwordx4 v[112:115], v90, s[40:41] offset:16
	global_load_dwordx4 v[116:119], v90, s[40:41]
	global_load_dwordx4 v[100:103], v[86:87], off offset:2080
	global_load_dwordx4 v[120:123], v90, s[40:41] offset:80
	global_load_dwordx4 v[124:127], v90, s[40:41] offset:64
	global_load_dwordx4 v[104:107], v[86:87], off offset:2112
	global_load_dwordx4 v[128:131], v90, s[40:41] offset:144
	global_load_dwordx4 v[132:135], v90, s[40:41] offset:128
	global_load_dwordx4 v[108:111], v[86:87], off offset:2144
	global_load_dwordx4 v[136:139], v90, s[40:41] offset:208
	global_load_dwordx4 v[140:143], v90, s[40:41] offset:192
	v_mov_b32_e32 v186, 0
	s_cmp_lt_i32 s59, 1
	s_barrier
	v_xor_b32_e32 v3, 2, v174
	v_cmp_lt_i32_e32 vcc, v3, v5
	s_nop 1
	v_cndmask_b32_e32 v3, v174, v3, vcc
	v_lshlrev_b32_e32 v159, 2, v3
	v_xor_b32_e32 v3, 4, v174
	v_cmp_lt_i32_e32 vcc, v3, v5
	s_nop 1
	v_cndmask_b32_e32 v3, v174, v3, vcc
	v_lshlrev_b32_e32 v184, 2, v3
	v_xor_b32_e32 v3, 32, v174
	v_cmp_lt_i32_e32 vcc, v3, v5
	s_nop 1
	v_cndmask_b32_e32 v3, v174, v3, vcc
	v_lshlrev_b32_e32 v187, 2, v3
	v_max_f32_e64 v2, |v2|, |v2|
	v_max_f32_e64 v0, |v0|, |v0|
	s_nop 0
	v_max_f32_dpp v2, v2, v2 quad_perm:[1,0,3,2] row_mask:0xf bank_mask:0xf
	v_max_f32_dpp v0, v0, v0 quad_perm:[1,0,3,2] row_mask:0xf bank_mask:0xf
	s_nop 0
	v_max_f32_dpp v2, v2, v2 quad_perm:[2,3,0,1] row_mask:0xf bank_mask:0xf
	v_max_f32_dpp v0, v0, v0 quad_perm:[2,3,0,1] row_mask:0xf bank_mask:0xf
	s_nop 0
	v_max_f32_dpp v2, v2, v2 row_half_mirror row_mask:0xf bank_mask:0xf
	v_max_f32_dpp v0, v0, v0 row_half_mirror row_mask:0xf bank_mask:0xf
	s_nop 0
	v_max_f32_dpp v2, v2, v2 row_mirror row_mask:0xf bank_mask:0xf
	v_max_f32_dpp v0, v0, v0 row_mirror row_mask:0xf bank_mask:0xf
	s_nop 0
	v_readlane_b32 s60, v2, 0
	v_readlane_b32 s61, v2, 16
	v_readlane_b32 s62, v2, 32
	v_readlane_b32 s63, v2, 48
	v_readlane_b32 s76, v0, 0
	v_readlane_b32 s77, v0, 16
	v_readlane_b32 s50, v0, 32
	v_readlane_b32 s51, v0, 48
	v_mov_b32_e32 v17, s60
	v_mov_b32_e32 v83, s76
	v_max_f32_e32 v17, s61, v17
	v_max_f32_e32 v83, s77, v83
	v_max_f32_e32 v17, s62, v17
	v_max_f32_e32 v83, s50, v83
	v_max_f32_e32 v17, s63, v17
	v_max_f32_e32 v83, s51, v83
	v_mul_f32_e32 v0, 0x41b8aa3b, v17
	v_fmaak_f32 v0, v83, v0, 0x42800000
	s_cbranch_scc1 .LBB0_270
	s_lshl_b32 s2, s58, 2
	s_add_i32 s2, s2, 0
	v_mov_b32_e32 v2, s2
	ds_read_b32 v2, v2
	v_mov_b32_e32 v186, 0
	s_mov_b64 s[2:3], 0
	v_mov_b32_e32 v3, s59
